# gg_phase: 32 fragment loads per block issued together, MFMA chain with counted waits (was load-wait-MFMA x64)
# speedup vs baseline: 1.0372x; 1.0107x over previous
; __device__ __forceinline__ void gg_phase(const Ctx& c, const bf16_t* xb, const bf16_t* wgg, float* gg) {
;     const int row = c.lane & 15, quad = c.lane >> 4;
;     for (int t = c.wave * c.G + c.bid; t < MTOK / 16; t += c.NGW) {
;         f32x4 acc = {0.f, 0.f, 0.f, 0.f};
;         const bf16_t* ap = xb + (size_t)(t * 16 + row) * DM + quad * 8; const bf16_t* bp = wgg + (size_t)row * DM + quad * 8;
; #pragma unroll 16
;         for (int k0 = 0; k0 < DM; k0 += 32) { const bf16x8 av = *(const bf16x8*)(ap + k0), bv = *(const bf16x8*)(bp + k0); acc = __builtin_amdgcn_mfma_f32_16x16x32_bf16(av, bv, acc, 0, 0, 0); }
; #pragma unroll
;         for (int j = 0; j < 4; ++j) gg[(size_t)(t * 16 + quad * 4 + j) * 16 + row] = acc[j];
;     }
; }
.LBB0_325:
	v_lshl_add_u64 v[18:19], v[14:15], 0, v[8:9]
	v_add_co_u32_e32 v18, vcc, 0x19d00000, v18
	v_lshl_add_u64 v[20:21], v[16:17], 0, v[8:9]
	s_nop 0
	v_addc_co_u32_e32 v19, vcc, 0, v19, vcc
	global_load_dwordx4 v[30:33], v[18:19], off
	global_load_dwordx4 v[94:97], v[20:21], off offset:-512
	global_load_dwordx4 v[34:37], v[18:19], off offset:64
	global_load_dwordx4 v[98:101], v[20:21], off offset:-448
	global_load_dwordx4 v[38:41], v[18:19], off offset:128
	global_load_dwordx4 v[102:105], v[20:21], off offset:-384
	global_load_dwordx4 v[42:45], v[18:19], off offset:192
	global_load_dwordx4 v[106:109], v[20:21], off offset:-320
	global_load_dwordx4 v[46:49], v[18:19], off offset:256
	global_load_dwordx4 v[110:113], v[20:21], off offset:-256
	global_load_dwordx4 v[50:53], v[18:19], off offset:320
	global_load_dwordx4 v[114:117], v[20:21], off offset:-192
	global_load_dwordx4 v[54:57], v[18:19], off offset:384
	global_load_dwordx4 v[118:121], v[20:21], off offset:-128
	global_load_dwordx4 v[58:61], v[18:19], off offset:448
	global_load_dwordx4 v[122:125], v[20:21], off offset:-64
	global_load_dwordx4 v[62:65], v[18:19], off offset:512
	global_load_dwordx4 v[126:129], v[20:21], off
	global_load_dwordx4 v[66:69], v[18:19], off offset:576
	global_load_dwordx4 v[130:133], v[20:21], off offset:64
	global_load_dwordx4 v[70:73], v[18:19], off offset:640
	global_load_dwordx4 v[134:137], v[20:21], off offset:128
	global_load_dwordx4 v[74:77], v[18:19], off offset:704
	global_load_dwordx4 v[138:141], v[20:21], off offset:192
	global_load_dwordx4 v[78:81], v[18:19], off offset:768
	global_load_dwordx4 v[142:145], v[20:21], off offset:256
	global_load_dwordx4 v[82:85], v[18:19], off offset:832
	global_load_dwordx4 v[146:149], v[20:21], off offset:320
	global_load_dwordx4 v[86:89], v[18:19], off offset:896
	global_load_dwordx4 v[150:153], v[20:21], off offset:384
	global_load_dwordx4 v[90:93], v[18:19], off offset:960
	global_load_dwordx4 v[156:159], v[20:21], off offset:448
	s_addk_i32 s4, 0x200
	v_lshl_add_u64 v[14:15], v[14:15], 0, s[82:83]
	v_lshl_add_u64 v[16:17], v[16:17], 0, s[82:83]
	s_cmpk_gt_u32 s4, 0x7df
	s_waitcnt vmcnt(30)
	v_mfma_f32_16x16x32_bf16 v[2:5], v[30:33], v[94:97], v[2:5]
	s_waitcnt vmcnt(28)
	v_mfma_f32_16x16x32_bf16 v[2:5], v[34:37], v[98:101], v[2:5]
	s_waitcnt vmcnt(26)
	v_mfma_f32_16x16x32_bf16 v[2:5], v[38:41], v[102:105], v[2:5]
	s_waitcnt vmcnt(24)
	v_mfma_f32_16x16x32_bf16 v[2:5], v[42:45], v[106:109], v[2:5]
	s_waitcnt vmcnt(22)
	v_mfma_f32_16x16x32_bf16 v[2:5], v[46:49], v[110:113], v[2:5]
	s_waitcnt vmcnt(20)
	v_mfma_f32_16x16x32_bf16 v[2:5], v[50:53], v[114:117], v[2:5]
	s_waitcnt vmcnt(18)
	v_mfma_f32_16x16x32_bf16 v[2:5], v[54:57], v[118:121], v[2:5]
	s_waitcnt vmcnt(16)
	v_mfma_f32_16x16x32_bf16 v[2:5], v[58:61], v[122:125], v[2:5]
	s_waitcnt vmcnt(14)
	v_mfma_f32_16x16x32_bf16 v[2:5], v[62:65], v[126:129], v[2:5]
	s_waitcnt vmcnt(12)
	v_mfma_f32_16x16x32_bf16 v[2:5], v[66:69], v[130:133], v[2:5]
	s_waitcnt vmcnt(10)
	v_mfma_f32_16x16x32_bf16 v[2:5], v[70:73], v[134:137], v[2:5]
	s_waitcnt vmcnt(8)
	v_mfma_f32_16x16x32_bf16 v[2:5], v[74:77], v[138:141], v[2:5]
	s_waitcnt vmcnt(6)
	v_mfma_f32_16x16x32_bf16 v[2:5], v[78:81], v[142:145], v[2:5]
	s_waitcnt vmcnt(4)
	v_mfma_f32_16x16x32_bf16 v[2:5], v[82:85], v[146:149], v[2:5]
	s_waitcnt vmcnt(2)
	v_mfma_f32_16x16x32_bf16 v[2:5], v[86:89], v[150:153], v[2:5]
	s_waitcnt vmcnt(0)
	v_mfma_f32_16x16x32_bf16 v[2:5], v[90:93], v[156:159], v[2:5]
	s_cbranch_scc0 .LBB0_325
	v_lshl_or_b32 v14, s2, 4, v0
	v_ashrrev_i32_e32 v15, 31, v14
	v_lshlrev_b64 v[16:17], 6, v[14:15]
	v_lshl_add_u64 v[16:17], v[6:7], 0, v[16:17]
	s_nop 2
	global_store_dword v[16:17], v2, off
	v_or_b32_e32 v16, 1, v14
	v_ashrrev_i32_e32 v17, 31, v16
	v_lshlrev_b64 v[16:17], 6, v[16:17]
	v_lshl_add_u64 v[16:17], v[6:7], 0, v[16:17]
	v_or_b32_e32 v2, 2, v14
	global_store_dword v[16:17], v3, off
	v_ashrrev_i32_e32 v3, 31, v2
	v_lshlrev_b64 v[2:3], 6, v[2:3]
	v_lshl_add_u64 v[2:3], v[6:7], 0, v[2:3]
	global_store_dword v[2:3], v4, off
	v_or_b32_e32 v2, 3, v14
	v_ashrrev_i32_e32 v3, 31, v2
	v_lshlrev_b64 v[2:3], 6, v[2:3]
	s_add_i32 s2, s2, s62
	v_lshl_add_u64 v[2:3], v[6:7], 0, v[2:3]
	s_cmpk_gt_i32 s2, 0x1ff
	v_add_u32_e32 v10, s3, v10
	global_store_dword v[2:3], v5, off
	s_cbranch_scc0 .LBB0_324
